# v13 + grid barrier: the agent-scope L1 invalidate moves from after the release flag to barrier arrival (no payload loads happen between arrival and release), post-flag invalidates removed
# speedup vs baseline: 1.0265x; 1.0265x over previous
.LBB0_1875:
	s_waitcnt vmcnt(0)
	s_waitcnt lgkmcnt(0)
	s_barrier
	s_mov_b64 s[0:1], exec
	v_readlane_b32 s20, v235, 3
	v_readlane_b32 s21, v235, 4
	s_and_b64 s[20:21], s[0:1], s[20:21]
	s_mov_b64 exec, s[20:21]
	s_cbranch_execz .LBB0_1934
	s_waitcnt vmcnt(0) expcnt(0) lgkmcnt(0)
	buffer_inv sc1
	ds_read_b32 v2, v166
	ds_read_b32 v0, v167
	s_waitcnt lgkmcnt(1)
	v_cmp_ne_u32_e32 vcc, 0, v2
	s_cbranch_vccnz .LBB0_1898
	s_mov_b32 s24, 1
	s_branch .LBB0_1880

.LBB0_1913:
	s_or_b64 exec, exec, s[28:29]
	s_waitcnt vmcnt(0)
	s_waitcnt vmcnt(0)

.LBB0_1931:
	s_or_b64 exec, exec, s[20:21]
	s_mov_b64 s[20:21], exec
	v_mbcnt_lo_u32_b32 v0, s20, 0
	v_mbcnt_hi_u32_b32 v0, s21, v0
	v_cmp_eq_u32_e32 vcc, 0, v0
	s_waitcnt vmcnt(0)
	s_and_saveexec_b64 s[28:29], vcc
	s_cbranch_execz .LBB0_1933
	s_bcnt1_i32_b64 s20, s[20:21]
	v_mov_b32_e32 v0, s20
	v_readlane_b32 s20, v233, 36
	v_readlane_b32 s21, v233, 37
	s_nop 4
	global_atomic_add v33, v0, s[20:21]
